# grid barrier: non-leader workgroups poll the top-level generation word directly (one polling hop less); unused per-XCD generation bump dropped
# baseline (speedup 1.0000x reference)
; __device__ __forceinline__ unsigned xb_ld(unsigned* p)              { return __hip_atomic_load(p, __ATOMIC_RELAXED, __HIP_MEMORY_SCOPE_AGENT); }
; __device__ __forceinline__ unsigned xb_add(unsigned* p, unsigned v) { return __hip_atomic_fetch_add(p, v, __ATOMIC_RELAXED, __HIP_MEMORY_SCOPE_AGENT); }
; #define XB_SPIN(cond, bar) do { unsigned _sp = 0; while (cond) { __builtin_amdgcn_s_sleep(1); \
;     if ((++_sp & 255u) == 0u) { if (xb_ld(&(bar)[XB_TMO])) break; if (_sp > XB_SPIN_CAP) { atomicAdd(&(bar)[XB_TMO], 1u); break; } } } } while (0)
; __device__ __forceinline__ void xcd_barrier(const XcdBarrier& b) {
;     ...
;         const unsigned old = xb_add(&bar[XB_XSUB(b.x)], 1u);
;         const unsigned gen = old / nloc;
;         if (old + 1u == (gen + 1u) * nloc) {
;             __builtin_amdgcn_fence(__ATOMIC_RELEASE, "agent");
;             asm volatile("s_waitcnt vmcnt(0)" ::: "memory");
;             const unsigned og = xb_add(&bar[XB_TOP], 1u);
;             const unsigned tg = og / nx;
;             if (og + 1u == (tg + 1u) * nx) xb_add(&bar[XB_TOPGEN], 1u);
;             else XB_SPIN(xb_ld(&bar[XB_TOPGEN]) == tg, bar);
;             __builtin_amdgcn_fence(__ATOMIC_ACQUIRE, "agent");
;             xb_add(&bar[XB_XGEN(b.x)], 1u);
;             asm volatile("s_waitcnt vmcnt(0)" ::: "memory");
;         } else {
;             XB_SPIN(xb_ld(&bar[XB_XGEN(b.x)]) == gen, bar);
.LBB0_162:
	s_or_b64 exec, exec, s[8:9]
	v_cvt_f32_u32_e32 v5, v3
	s_waitcnt vmcnt(0)
	v_readfirstlane_b32 s3, v4
	v_sub_u32_e32 v4, 0, v3
	v_rcp_iflag_f32_e32 v5, v5
	v_add_u32_e32 v6, s3, v0
	v_mul_f32_e32 v5, 0x4f7ffffe, v5
	v_cvt_u32_f32_e32 v5, v5
	v_mul_lo_u32 v0, v4, v5
	v_mul_hi_u32 v0, v5, v0
	v_add_u32_e32 v0, v5, v0
	v_mul_hi_u32 v0, v6, v0
	v_mul_lo_u32 v4, v0, v3
	v_sub_u32_e32 v4, v6, v4
	v_add_u32_e32 v5, 1, v0
	v_cmp_ge_u32_e32 vcc, v4, v3
	s_nop 1
	v_cndmask_b32_e32 v0, v0, v5, vcc
	v_sub_u32_e32 v5, v4, v3
	v_cndmask_b32_e32 v4, v4, v5, vcc
	v_add_u32_e32 v5, 1, v0
	v_cmp_ge_u32_e32 vcc, v4, v3
	v_add_u32_e32 v4, 1, v6
	s_nop 0
	v_cndmask_b32_e32 v0, v0, v5, vcc
	v_mul_lo_u32 v5, v3, v0
	v_add_u32_e32 v3, v5, v3
	v_cmp_ne_u32_e32 vcc, v4, v3
	s_and_saveexec_b64 s[8:9], vcc
	s_xor_b64 s[8:9], exec, s[8:9]
	s_cbranch_execz .LBB0_176
	v_readlane_b32 s14, v253, 51
	v_readlane_b32 s15, v253, 52
	s_waitcnt lgkmcnt(0)
	s_nop 3
	global_load_dword v2, v1, s[14:15] sc1
	s_waitcnt vmcnt(0)
	v_cmp_eq_u32_e32 vcc, v2, v0
	s_and_saveexec_b64 s[14:15], vcc
	s_cbranch_execz .LBB0_175
	s_mov_b32 s3, 1
	s_mov_b64 s[16:17], 0
	s_branch .LBB0_166

; __device__ __forceinline__ unsigned xb_add(unsigned* p, unsigned v) { return __hip_atomic_fetch_add(p, v, __ATOMIC_RELAXED, __HIP_MEMORY_SCOPE_AGENT); }
; __device__ __forceinline__ void xcd_barrier(const XcdBarrier& b) {
;     ...
;             __builtin_amdgcn_fence(__ATOMIC_ACQUIRE, "agent");
;             xb_add(&bar[XB_XGEN(b.x)], 1u);
.LBB0_193:
	s_or_b64 exec, exec, s[8:9]
	s_mov_b64 s[8:9], exec
	v_mbcnt_lo_u32_b32 v0, s8, 0
	v_mbcnt_hi_u32_b32 v0, s9, v0
	v_cmp_eq_u32_e32 vcc, 0, v0
	s_waitcnt vmcnt(0)
	buffer_inv sc1
	s_and_saveexec_b64 s[14:15], vcc
	s_cbranch_execz .LBB0_195
	s_bcnt1_i32_b64 s3, s[8:9]
	v_readlane_b32 s8, v253, 47
	v_mov_b32_e32 v0, s3
	v_readlane_b32 s9, v253, 48
	s_nop 4
	s_nop 0

; __device__ __forceinline__ unsigned xb_ld(unsigned* p)              { return __hip_atomic_load(p, __ATOMIC_RELAXED, __HIP_MEMORY_SCOPE_AGENT); }
; __device__ __forceinline__ unsigned xb_add(unsigned* p, unsigned v) { return __hip_atomic_fetch_add(p, v, __ATOMIC_RELAXED, __HIP_MEMORY_SCOPE_AGENT); }
; #define XB_SPIN(cond, bar) do { unsigned _sp = 0; while (cond) { __builtin_amdgcn_s_sleep(1); \
;     if ((++_sp & 255u) == 0u) { if (xb_ld(&(bar)[XB_TMO])) break; if (_sp > XB_SPIN_CAP) { atomicAdd(&(bar)[XB_TMO], 1u); break; } } } } while (0)
; __device__ __forceinline__ void xcd_barrier(const XcdBarrier& b) {
;     ...
;         const unsigned old = xb_add(&bar[XB_XSUB(b.x)], 1u);
;         const unsigned gen = old / nloc;
;         if (old + 1u == (gen + 1u) * nloc) {
;             __builtin_amdgcn_fence(__ATOMIC_RELEASE, "agent");
;             asm volatile("s_waitcnt vmcnt(0)" ::: "memory");
;             const unsigned og = xb_add(&bar[XB_TOP], 1u);
;             const unsigned tg = og / nx;
;             if (og + 1u == (tg + 1u) * nx) xb_add(&bar[XB_TOPGEN], 1u);
;             else XB_SPIN(xb_ld(&bar[XB_TOPGEN]) == tg, bar);
;             __builtin_amdgcn_fence(__ATOMIC_ACQUIRE, "agent");
;             xb_add(&bar[XB_XGEN(b.x)], 1u);
;             asm volatile("s_waitcnt vmcnt(0)" ::: "memory");
;         } else {
;             XB_SPIN(xb_ld(&bar[XB_XGEN(b.x)]) == gen, bar);
.LBB0_608:
	s_or_b64 exec, exec, s[6:7]
	v_cvt_f32_u32_e32 v5, v3
	s_waitcnt vmcnt(0)
	v_readfirstlane_b32 s2, v4
	v_sub_u32_e32 v4, 0, v3
	v_rcp_iflag_f32_e32 v5, v5
	v_add_u32_e32 v6, s2, v0
	v_mul_f32_e32 v5, 0x4f7ffffe, v5
	v_cvt_u32_f32_e32 v5, v5
	v_mul_lo_u32 v0, v4, v5
	v_mul_hi_u32 v0, v5, v0
	v_add_u32_e32 v0, v5, v0
	v_mul_hi_u32 v0, v6, v0
	v_mul_lo_u32 v4, v0, v3
	v_sub_u32_e32 v4, v6, v4
	v_add_u32_e32 v5, 1, v0
	v_cmp_ge_u32_e32 vcc, v4, v3
	s_nop 1
	v_cndmask_b32_e32 v0, v0, v5, vcc
	v_sub_u32_e32 v5, v4, v3
	v_cndmask_b32_e32 v4, v4, v5, vcc
	v_add_u32_e32 v5, 1, v0
	v_cmp_ge_u32_e32 vcc, v4, v3
	v_add_u32_e32 v4, 1, v6
	s_nop 0
	v_cndmask_b32_e32 v0, v0, v5, vcc
	v_mul_lo_u32 v5, v3, v0
	v_add_u32_e32 v3, v5, v3
	v_cmp_ne_u32_e32 vcc, v4, v3
	s_and_saveexec_b64 s[2:3], vcc
	s_xor_b64 s[6:7], exec, s[2:3]
	s_cbranch_execz .LBB0_622
	v_readlane_b32 s2, v253, 51
	v_readlane_b32 s3, v253, 52
	s_waitcnt lgkmcnt(0)
	s_nop 3
	global_load_dword v2, v1, s[2:3] sc1
	s_waitcnt vmcnt(0)
	v_cmp_eq_u32_e32 vcc, v2, v0
	s_and_saveexec_b64 s[8:9], vcc
	s_cbranch_execz .LBB0_621
	s_mov_b32 s2, 1
	s_mov_b64 s[14:15], 0
	s_branch .LBB0_612

; __device__ __forceinline__ unsigned xb_add(unsigned* p, unsigned v) { return __hip_atomic_fetch_add(p, v, __ATOMIC_RELAXED, __HIP_MEMORY_SCOPE_AGENT); }
; __device__ __forceinline__ void xcd_barrier(const XcdBarrier& b) {
;     ...
;             __builtin_amdgcn_fence(__ATOMIC_ACQUIRE, "agent");
;             xb_add(&bar[XB_XGEN(b.x)], 1u);
.LBB0_639:
	s_or_b64 exec, exec, s[6:7]
	s_mov_b64 s[6:7], exec
	v_mbcnt_lo_u32_b32 v0, s6, 0
	v_mbcnt_hi_u32_b32 v0, s7, v0
	v_cmp_eq_u32_e32 vcc, 0, v0
	s_waitcnt vmcnt(0)
	buffer_inv sc1
	s_and_saveexec_b64 s[8:9], vcc
	s_cbranch_execz .LBB0_641
	s_bcnt1_i32_b64 s2, s[6:7]
	v_mov_b32_e32 v0, s2
	v_readlane_b32 s2, v253, 47
	v_readlane_b32 s3, v253, 48
	s_nop 4
	s_nop 0

; __device__ __forceinline__ unsigned xb_add(unsigned* p, unsigned v) { return __hip_atomic_fetch_add(p, v, __ATOMIC_RELAXED, __HIP_MEMORY_SCOPE_AGENT); }
; __device__ __forceinline__ void xcd_barrier(const XcdBarrier& b) {
;     ...
;             __builtin_amdgcn_fence(__ATOMIC_ACQUIRE, "agent");
;             xb_add(&bar[XB_XGEN(b.x)], 1u);
.LBB0_853:
	s_or_b64 exec, exec, s[6:7]
	s_mov_b64 s[6:7], exec
	v_mbcnt_lo_u32_b32 v0, s6, 0
	v_mbcnt_hi_u32_b32 v0, s7, v0
	v_cmp_eq_u32_e32 vcc, 0, v0
	s_waitcnt vmcnt(0)
	buffer_inv sc1
	s_and_saveexec_b64 s[8:9], vcc
	s_cbranch_execz .LBB0_137
	s_bcnt1_i32_b64 s2, s[6:7]
	v_mov_b32_e32 v0, s2
	v_readlane_b32 s2, v253, 47
	v_readlane_b32 s3, v253, 48
	s_nop 4
	s_nop 0
	s_branch .LBB0_137

; __device__ __forceinline__ unsigned xb_add(unsigned* p, unsigned v) { return __hip_atomic_fetch_add(p, v, __ATOMIC_RELAXED, __HIP_MEMORY_SCOPE_AGENT); }
; __device__ __forceinline__ void xcd_barrier(const XcdBarrier& b) {
;     ...
;             __builtin_amdgcn_fence(__ATOMIC_ACQUIRE, "agent");
;             xb_add(&bar[XB_XGEN(b.x)], 1u);
.LBB0_1067:
	s_bcnt1_i32_b64 s2, s[6:7]
	v_mov_b32_e32 v0, s2
	v_readlane_b32 s2, v253, 47
	v_readlane_b32 s3, v253, 48
	s_nop 4
	s_nop 0
	s_getpc_b64 s[98:99]
